# adds: stage-load drain (vmcnt 0) moved to the very start of every tile epilogue, ahead of the rst table compute
# speedup vs baseline: 1.0101x; 1.0101x over previous
; __device__ __forceinline__ int opaque_tid() { int t = threadIdx.x; asm volatile("" : "+v"(t)); return t; }
;     __device__ __forceinline__ void operator()(AccRef acc, const pg8::Unit& u, int wr, int wc, int fr, int fq) const {
;     ...
;         if (kind == 0 || kind == 2 || kind == 4) {
;             const int t = opaque_tid();
;             if (t < 256) rst[t] = row_rs(rss_in, u.pm * 256 + t);
;             __syncthreads();
;         }
;         if (kind == 0) { EpiSwiglu E{(bf16*)big, rst}; E(acc, u, wr, wc, fr, fq); }
;         else if (kind == 1) { EpiResid E{(bf16*)(ws + WS_HN), outf, scale, rss_out}; E(acc, u, wr, wc, fr, fq); }
;         else if (kind == 2) {
;             const int l = layer;
;             EpiQKV E{big, pp->in[9] + l * 64, pp->in[10] + l * 64, pp->in[13] + l * 64, pp->in[14] + l * 64, pp->in[15] + l * 64, pp->in[16] + l * 64, pp->in[8] + l * 6, (float*)(ws + WS_LOGF), rst};
;             E(acc, u, wr, wc, fr, fq);
;         }
;         else if (kind == 3) { EpiPStore E{(v4u*)(big + B_P)}; E(acc, u, wr, wc, fr, fq); }
;         else { EpiGate E{pp->in[7] + (size_t)layer * 4 * D + (size_t)bi * D, (const v4u*)(big + B_P), (v4u*)(big + B_TMP), (bf16*)(big + B_MRG), bi == 0, bi == 3, rst}; E(acc, u, wr, wc, fr, fq); }
.LBB0_171:
	s_waitcnt vmcnt(0)
	v_mov_b32_e32 v245, v240
	v_mov_b32_e32 v244, v241
	s_mov_b64 s[8:9], -1
	s_mov_b64 s[96:97], 0
	s_cmp_lt_i32 s15, 3
	s_mov_b64 s[10:11], 0
	s_mov_b64 s[6:7], 0
	s_cbranch_scc1 .LBB0_173
	s_cmp_lg_u32 s15, 3
	s_mov_b64 s[8:9], 0
	s_mov_b64 s[10:11], -1
	s_cselect_b64 s[6:7], -1, 0
